# P3: the per-lane 128x128 decay mask values (32 x [sub,sub,max,cvt,cmp,cndmask,mul,exp]) depend only on lane and head; computed by a CU's first unit and kept in v213,v219..v249 for its later units (sam
# speedup vs baseline: 1.0019x; 1.0008x over previous
; #define LAS __attribute__((address_space(3)))
; #define RT_LOAD(u_) do { const size_t tokc_ = (size_t)((u_) >> 2) * 128; const int h_ = (u_) & 3; \
;         _Pragma("unroll") for (int i = 0; i < 4; ++i) { const int idx = tid + 512 * i; const size_t src = (tokc_ + (idx >> 4)) * 512 + h_ * 128 + 8 * (idx & 15); \
;             rq[i] = *(const u32x4*)(QR + src); rk[i] = *(const u32x4*)(KR + src); rv[i] = *(const u32x4*)(VR + src); } } while (0)
; __device__ __forceinline__ void ret_phase(const Params& P, LAS unsigned char* lds, int tid, int lane, int wave, int bid, int G) {
;     const bf16_t* PJ = (const bf16_t*)(P.ws + OFF_PROJ);
;     const bf16_t* QR = PJ + 4 * SEC_STRIDE; const bf16_t* KR = PJ + 5 * SEC_STRIDE; const bf16_t* VR = PJ + 6 * SEC_STRIDE; const bf16_t* GR = PJ + 7 * SEC_STRIDE;
;     const bf16_t* ST = (const bf16_t*)(P.ws + OFF_ST); const bf16_t* FIN = (const bf16_t*)(P.ws + OFF_FIN); bf16_t* MIX = (bf16_t*)(P.ws + OFF_MIX);
;     LAS unsigned char* Qt = lds; LAS unsigned char* Kt = lds + 32768; LAS unsigned char* Vt = lds + 65536; LAS unsigned char* Pt = lds + 98304;
;     int g = lane >> 4, l15 = lane & 15, q4 = l15 >> 2, p = lane & 3, w16 = wave * 16;
;     ...
;     int u = bid; if (u >= RET_UNITS) return;
;     u32x4 rq[4], rk[4], rv[4];
;     ...
;     RT_LOAD(u);
;     for (; u < RET_UNITS; u += G) {
;         const int gc = u >> 2, h = u & 3; const size_t tokc = (size_t)gc * 128;
;         const float lgf2 = -__expf(P.dec_f[h]) * LOG2E, lgb2 = -__expf(P.dec_b[h]) * LOG2E;
.LBB0_380:
	s_cmp_lt_i32 s28, 5
	s_cselect_b64 s[6:7], -1, 0
	s_and_b64 s[0:1], s[6:7], s[0:1]
	s_andn2_b64 vcc, exec, s[0:1]
	s_cbranch_vccnz .LBB0_393
	s_cmpk_gt_i32 s2, 0x9ff
	s_cbranch_scc1 .LBB0_393
	s_and_b32 s84, s3, 3
	s_cmp_eq_u32 s84, 0
	s_cselect_b64 s[86:87], -1, 0
	s_mov_b64 s[84:85], 0
	s_add_u32 s10, s22, 0x20000000
	s_addc_u32 s11, s23, 0
	s_add_u32 s12, s22, 0x25000000
	s_addc_u32 s13, s23, 0
	s_add_u32 s14, s22, 0x2a000000
	s_addc_u32 s15, s23, 0
	s_add_u32 s21, s22, 0x2f000000
	s_addc_u32 s25, s23, 0
	s_add_u32 s44, s22, 0x34000000
	v_lshlrev_b32_e32 v1, 3, v0
	s_addc_u32 s45, s23, 0
	v_lshlrev_b32_e32 v74, 5, v0
	v_and_b32_e32 v106, 0x78, v1
	s_movk_i32 s0, 0x7e00
	v_mov_b32_e32 v1, 0x4000
	s_add_u32 s16, s22, 0x3e000000
	v_bitop3_b32 v110, v74, s0, v1 bitop3:0xc8
	s_mov_b32 s0, 0xfe00
	v_mov_b32_e32 v1, 0xc000
	s_addc_u32 s17, s23, 0
	v_bitop3_b32 v114, v74, s0, v1 bitop3:0xc8
	s_ashr_i32 s0, s2, 2
	s_ashr_i32 s1, s0, 31
	s_lshl_b32 s4, s2, 7
	s_lshl_b64 s[0:1], s[0:1], 16
	s_and_b32 s4, s4, 0x180
	s_or_b32 s0, s0, s4
	v_and_b32_e32 v108, 0x3e00, v74
	v_or_b32_e32 v1, s0, v106
	v_or_b32_e32 v2, v1, v108
	v_mov_b32_e32 v3, s1
	v_or_b32_e32 v112, 0x8000, v108
	v_lshlrev_b64 v[4:5], 1, v[2:3]
	v_or_b32_e32 v2, v1, v110
	v_lshl_add_u64 v[50:51], s[10:11], 0, v[4:5]
	v_lshl_add_u64 v[52:53], s[12:13], 0, v[4:5]
	v_lshl_add_u64 v[54:55], s[14:15], 0, v[4:5]
	v_lshlrev_b64 v[4:5], 1, v[2:3]
	v_or_b32_e32 v2, v1, v112
	v_lshl_add_u64 v[56:57], s[10:11], 0, v[4:5]
	v_lshl_add_u64 v[58:59], s[12:13], 0, v[4:5]
	v_lshl_add_u64 v[60:61], s[14:15], 0, v[4:5]
	v_lshlrev_b64 v[4:5], 1, v[2:3]
	v_or_b32_e32 v2, v1, v114
	v_lshlrev_b64 v[2:3], 1, v[2:3]
	v_lshl_add_u64 v[72:73], s[14:15], 0, v[2:3]
	v_lshl_add_u64 v[62:63], s[10:11], 0, v[4:5]
	v_lshl_add_u64 v[64:65], s[12:13], 0, v[4:5]
	v_lshl_add_u64 v[66:67], s[14:15], 0, v[4:5]
	v_lshl_add_u64 v[68:69], s[10:11], 0, v[2:3]
	v_lshl_add_u64 v[70:71], s[12:13], 0, v[2:3]
	global_load_dwordx4 v[42:45], v[72:73], off
	global_load_dwordx4 v[46:49], v[70:71], off
	global_load_dwordx4 v[38:41], v[68:69], off
	global_load_dwordx4 v[34:37], v[66:67], off
	global_load_dwordx4 v[26:29], v[64:65], off
	global_load_dwordx4 v[30:33], v[62:63], off
	global_load_dwordx4 v[18:21], v[60:61], off
	global_load_dwordx4 v[22:25], v[58:59], off
	global_load_dwordx4 v[14:17], v[56:57], off
	global_load_dwordx4 v[10:13], v[54:55], off
	global_load_dwordx4 v[2:5], v[52:53], off
	global_load_dwordx4 v[6:9], v[50:51], off
	v_lshrrev_b32_e32 v54, 2, v0
	v_and_b32_e32 v1, 15, v0
	v_bfe_u32 v50, v0, 6, 2
	v_and_b32_e32 v54, 12, v54
	v_bitop3_b32 v50, v54, v1, v50 bitop3:0x36
	v_lshlrev_b32_e32 v116, 4, v0
	v_lshlrev_b32_e32 v50, 4, v50
	s_movk_i32 s0, 0x1f00
	v_or_b32_e32 v54, 0x200, v0
	v_and_or_b32 v107, v116, s0, v50
	v_lshlrev_b32_e32 v55, 4, v54
	s_movk_i32 s0, 0x3f00
	v_lshlrev_b32_e32 v51, 1, v0
	v_and_or_b32 v109, v55, s0, v50
	v_or_b32_e32 v56, 0x6000, v116
	s_movk_i32 s0, 0x7f00
	v_and_b32_e32 v51, 14, v51
	v_and_or_b32 v111, v56, s0, v50
	v_lshrrev_b32_e32 v56, 1, v0
	v_bfe_u32 v52, v0, 5, 2
	v_or_b32_e32 v53, 1, v51
	v_and_b32_e32 v56, 12, v56
	v_bitop3_b32 v51, v56, v51, v52 bitop3:0x36
	v_bitop3_b32 v52, v56, v53, v52 bitop3:0x36
	v_and_b32_e32 v50, 0x3f00, v74
	v_lshlrev_b32_e32 v51, 4, v51
	v_lshlrev_b32_e32 v52, 4, v52
	v_lshlrev_b32_e32 v53, 5, v54
	v_mov_b32_e32 v115, 0
	v_or_b32_e32 v57, v51, v50
	v_or_b32_e32 v50, v52, v50
	v_and_b32_e32 v53, 0x7f00, v53
	v_or_b32_e32 v55, 0x4000, v107
	v_mov_b32_e32 v117, v115
	v_or_b32_e32 v51, v51, v53
	v_or_b32_e32 v52, v52, v53
	s_add_i32 s48, 0, 0x10000
	v_add_u32_e32 v129, 0, v50
	v_mbcnt_lo_u32_b32 v50, -1, 0
	s_lshl_b32 s46, s97, 4
	s_mov_b32 s19, 0
	s_mov_b32 s47, 0x8000
	v_lshrrev_b32_e32 v118, 4, v180
	v_bfe_u32 v113, v0, 2, 2
	v_and_b32_e32 v126, 3, v0
	v_lshl_add_u64 v[120:121], s[16:17], 0, v[116:117]
	v_add_u32_e32 v127, s48, v55
	s_movk_i32 s49, 0x2000
	s_mov_b32 s50, 0xa000
	s_add_i32 s51, 0, 0x18000
	s_mov_b32 s52, 0xc2fc0000
	v_add_u32_e32 v128, 0, v57
	v_add_u32_e32 v130, 0, v51
	v_add_u32_e32 v131, 0, v52
	s_movk_i32 s53, 0x3000
	s_brev_b32 s20, 60
	s_mov_b32 s24, 0x358637bd
	s_mov_b32 s54, 0x800000
	s_brev_b32 s55, 64
	v_mov_b32_e32 v132, 0x42800000
	v_not_b32_e32 v133, 63
	v_mbcnt_hi_u32_b32 v134, -1, v50
	s_mov_b32 s56, s2
	s_mov_b32 s26, s2
	s_and_b32 s57, s26, 3
	s_lshl_b32 s0, s57, 2
	v_mov_b32_e32 v50, s0
	global_load_dword v104, v50, s[58:59]
	global_load_dword v105, v50, s[60:61]
	v_add_u32_e32 v50, 0, v107
	v_add_u32_e32 v51, s48, v107
	s_waitcnt vmcnt(0)
	s_branch .Lp3_common

; #define LAS __attribute__((address_space(3)))
; __device__ __forceinline__ f32x4 mfma16(bf16x8 a, bf16x8 b, f32x4 c) { return __builtin_amdgcn_mfma_f32_16x16x32_bf16(a, b, c, 0, 0, 0); }
; #define LBAR() asm volatile("s_waitcnt lgkmcnt(0)\n\ts_barrier" ::: "memory")
; #define OPQ_ALL() do { asm volatile("" : "+v"(g), "+v"(l15), "+v"(q4), "+v"(p)); } while (0)
; __device__ __forceinline__ void ret_phase(const Params& P, LAS unsigned char* lds, int tid, int lane, int wave, int bid, int G) {
;     ...
;         const int gc = u >> 2, h = u & 3; const size_t tokc = (size_t)gc * 128;
;         const float lgf2 = -__expf(P.dec_f[h]) * LOG2E, lgb2 = -__expf(P.dec_b[h]) * LOG2E;
; #pragma unroll
;         for (int i = 0; i < 4; ++i) { const int idx = tid + 512 * i; const unsigned d = off256(idx >> 4, idx & 15);
;             *(LAS u32x4*)(Qt + d) = rq[i]; *(LAS u32x4*)(Kt + d) = rk[i]; *(LAS u32x4*)(Vt + d) = rv[i]; }
;         LBAR();
;         const bf16_t* Sf = ST + ((size_t)(gc * 4 + h) * 2 + 0) * 16384; const bf16_t* Sb = Sf + 16384;
;         u32x4 rsf[2], rsb[2];
; #pragma unroll
;         for (int j = 0; j < 2; ++j) { const int idx = tid + 512 * j; rsf[j] = *(const u32x4*)((const unsigned char*)Sf + 16 * idx); rsb[j] = *(const u32x4*)((const unsigned char*)Sb + 16 * idx); }
;         OPQ_ALL();
;         bf16x8 qf[4];
; #pragma unroll
;         for (int ks = 0; ks < 4; ++ks) qf[ks] = *(const LAS bf16x8*)(Qt + off256(w16 + l15, 4 * ks + g));
;         {
;             const int n = w16 + l15;
;             f32x4 sa[8];
; #pragma unroll
;             for (int mt = 0; mt < 8; ++mt) {
;                 f32x4 a = (f32x4){0.f, 0.f, 0.f, 0.f};
; #pragma unroll
;                 for (int ks = 0; ks < 4; ++ks) a = mfma16(*(const LAS bf16x8*)(Kt + off256(16 * mt + l15, 4 * ks + g)), qf[ks], a);
;                 sa[mt] = a; }
; #pragma unroll
;             for (int mt = 0; mt < 8; ++mt) {
;                 const f32x4 a = sa[mt];
;                 float e[4];
; #pragma unroll
;                 for (int i = 0; i < 4; ++i) { const int m = 16 * mt + 4 * g + i, df = n - m; const float f = __builtin_amdgcn_exp2f(df >= 0 ? lgf2 * (float)df : lgb2 * (float)(-df)); e[i] = a[i] * f; }
.Lp3_common:
	ds_write_b128 v50, v[6:9]
	ds_write_b128 v50, v[2:5] offset:32768
	ds_write_b128 v51, v[10:13]
	v_add_u32_e32 v51, 0, v109
	s_ashr_i32 s27, s26, 31
	s_ashr_i32 s40, s26, 2
	ds_write_b128 v51, v[14:17]
	ds_write_b128 v51, v[22:25] offset:32768
	v_add_u32_e32 v51, s48, v109
	s_lshl_b64 s[0:1], s[26:27], 16
	ds_write_b128 v51, v[18:21]
	ds_write_b128 v50, v[30:33] offset:16384
	ds_write_b128 v50, v[26:29] offset:49152
	ds_write_b128 v127, v[34:37]
	v_add_u32_e32 v50, 0, v111
	s_add_u32 s0, s44, s0
	ds_write_b128 v50, v[38:41]
	ds_write_b128 v50, v[46:49] offset:32768
	v_add_u32_e32 v50, s48, v111
	s_addc_u32 s1, s45, s1
	ds_write_b128 v50, v[42:45]
	v_lshl_add_u64 v[50:51], s[0:1], 0, v[116:117]
	v_add_co_u32_e32 v52, vcc, s47, v50
	s_waitcnt lgkmcnt(0)
	s_barrier
	v_lshl_add_u32 v214, s57, 7, v1
	v_ashrrev_i32_e32 v215, 31, v214
	v_lshl_add_u64 v[214:215], v[214:215], 2, s[62:63]
	global_load_dword v205, v[214:215], off
	global_load_dword v206, v[214:215], off offset:64
	global_load_dword v207, v[214:215], off offset:128
	global_load_dword v208, v[214:215], off offset:192
	global_load_dword v209, v[214:215], off offset:256
	global_load_dword v210, v[214:215], off offset:320
	global_load_dword v211, v[214:215], off offset:384
	global_load_dword v212, v[214:215], off offset:448
	s_cmpk_lt_i32 s40, 0x200
	s_nop 0
	v_addc_co_u32_e32 v53, vcc, 0, v51, vcc
	global_load_dwordx4 v[68:71], v[50:51], off
	global_load_dwordx4 v[76:79], v[52:53], off
	v_add_co_u32_e32 v52, vcc, s49, v50
	v_mul_f32_e32 v104, 0x3fb8aa3b, v104
	s_nop 0
	v_addc_co_u32_e32 v53, vcc, 0, v51, vcc
	v_add_co_u32_e32 v50, vcc, s50, v50
	v_mul_f32_e32 v105, 0x3fb8aa3b, v105
	s_nop 0
	v_addc_co_u32_e32 v51, vcc, 0, v51, vcc
	global_load_dwordx4 v[84:87], v[52:53], off
	global_load_dwordx4 v[92:95], v[50:51], off
	v_exp_f32_e32 v104, v104
	v_lshlrev_b32_e32 v50, 2, v1
	v_add_u32_e32 v119, s46, v1
	v_and_b32_e32 v66, 12, v50
	v_bfe_u32 v67, v1, 2, 2
	v_lshlrev_b32_e32 v135, 8, v119
	v_bitop3_b32 v50, v66, v118, v67 bitop3:0x36
	v_add_u32_e32 v52, 4, v118
	v_add_u32_e32 v100, 0, v135
	v_lshlrev_b32_e32 v50, 4, v50
	v_bitop3_b32 v52, v66, v52, v67 bitop3:0x36
	v_add_u32_e32 v51, v100, v50
	v_lshlrev_b32_e32 v72, 4, v52
	v_add_u32_e32 v52, v100, v72
	ds_read_b128 v[58:61], v51
	ds_read_b128 v[54:57], v52
	v_add_u32_e32 v51, 8, v118
	v_lshl_add_u32 v122, v1, 8, 0
	v_bitop3_b32 v51, v66, v51, v67 bitop3:0x36
	v_add_u32_e32 v156, v122, v50
	v_lshlrev_b32_e32 v80, 4, v51
	ds_read_b128 v[50:53], v156 offset:32768
	v_add_u32_e32 v157, v122, v72
	ds_read_b128 v[72:75], v157 offset:32768
	v_add_u32_e32 v62, v100, v80
	ds_read_b128 v[62:65], v62
	s_waitcnt lgkmcnt(2)
	v_mfma_f32_16x16x32_bf16 v[50:53], v[50:53], v[58:61], 0
	v_add_u32_e32 v158, v122, v80
	v_add_u32_e32 v96, 12, v118
	ds_read_b128 v[80:83], v158 offset:32768
	ds_read_b128 v[88:91], v156 offset:36864
	s_waitcnt lgkmcnt(3)
	v_mfma_f32_16x16x32_bf16 v[72:75], v[72:75], v[54:57], v[50:53]
	v_bitop3_b32 v96, v66, v96, v67 bitop3:0x36
	v_lshlrev_b32_e32 v123, 4, v96
	ds_read_b128 v[96:99], v157 offset:36864
	v_add_u32_e32 v50, v100, v123
	v_add_u32_e32 v159, v122, v123
	ds_read_b128 v[50:53], v50
	ds_read_b128 v[100:103], v158 offset:36864
	s_waitcnt lgkmcnt(4)
	v_mfma_f32_16x16x32_bf16 v[72:75], v[80:83], v[62:65], v[72:75]
	ds_read_b128 v[80:83], v159 offset:32768
	ds_read_b128 v[122:125], v159 offset:36864
	s_waitcnt lgkmcnt(1)
	v_mfma_f32_16x16x32_bf16 v[136:139], v[80:83], v[50:53], v[72:75]
	v_mfma_f32_16x16x32_bf16 v[72:75], v[88:91], v[58:61], 0
	v_mfma_f32_16x16x32_bf16 v[72:75], v[96:99], v[54:57], v[72:75]
	v_mfma_f32_16x16x32_bf16 v[72:75], v[100:103], v[62:65], v[72:75]
	s_waitcnt lgkmcnt(0)
	v_mfma_f32_16x16x32_bf16 v[122:125], v[122:125], v[50:53], v[72:75]
	s_nop 5
	ds_read_b128 v[72:75], v156 offset:40960
	ds_read_b128 v[80:83], v156 offset:45056
	ds_read_b128 v[88:91], v157 offset:40960
	ds_read_b128 v[96:99], v157 offset:45056
	s_waitcnt lgkmcnt(3)
	v_mfma_f32_16x16x32_bf16 v[72:75], v[72:75], v[58:61], 0
	s_waitcnt lgkmcnt(1)
	v_mfma_f32_16x16x32_bf16 v[72:75], v[88:91], v[54:57], v[72:75]
	ds_read_b128 v[88:91], v158 offset:40960
	ds_read_b128 v[100:103], v158 offset:45056
	s_waitcnt lgkmcnt(1)
	v_mfma_f32_16x16x32_bf16 v[72:75], v[88:91], v[62:65], v[72:75]
	ds_read_b128 v[88:91], v159 offset:40960
	ds_read_b128 v[140:143], v159 offset:45056
	s_waitcnt lgkmcnt(1)
	v_mfma_f32_16x16x32_bf16 v[144:147], v[88:91], v[50:53], v[72:75]
	v_mfma_f32_16x16x32_bf16 v[72:75], v[80:83], v[58:61], 0
	v_mfma_f32_16x16x32_bf16 v[72:75], v[96:99], v[54:57], v[72:75]
	v_mfma_f32_16x16x32_bf16 v[72:75], v[100:103], v[62:65], v[72:75]
	s_waitcnt lgkmcnt(0)
	v_mfma_f32_16x16x32_bf16 v[100:103], v[140:143], v[50:53], v[72:75]
	s_nop 5
	ds_read_b128 v[72:75], v156 offset:49152
	ds_read_b128 v[80:83], v156 offset:53248
	ds_read_b128 v[88:91], v157 offset:49152
	ds_read_b128 v[140:143], v157 offset:53248
	s_waitcnt lgkmcnt(3)
	v_mfma_f32_16x16x32_bf16 v[72:75], v[72:75], v[58:61], 0
	s_waitcnt lgkmcnt(1)
	v_mfma_f32_16x16x32_bf16 v[72:75], v[88:91], v[54:57], v[72:75]
	ds_read_b128 v[88:91], v158 offset:49152
	ds_read_b128 v[148:151], v158 offset:53248
	s_waitcnt lgkmcnt(1)
	v_mfma_f32_16x16x32_bf16 v[72:75], v[88:91], v[62:65], v[72:75]
	ds_read_b128 v[88:91], v159 offset:49152
	ds_read_b128 v[152:155], v159 offset:53248
	s_waitcnt lgkmcnt(1)
	v_mfma_f32_16x16x32_bf16 v[96:99], v[88:91], v[50:53], v[72:75]
	v_mfma_f32_16x16x32_bf16 v[72:75], v[80:83], v[58:61], 0
	v_mfma_f32_16x16x32_bf16 v[72:75], v[140:143], v[54:57], v[72:75]
	v_mfma_f32_16x16x32_bf16 v[72:75], v[148:151], v[62:65], v[72:75]
	s_waitcnt lgkmcnt(0)
	v_mfma_f32_16x16x32_bf16 v[88:91], v[152:155], v[50:53], v[72:75]
	s_nop 5
	ds_read_b128 v[72:75], v156 offset:57344
	ds_read_b128 v[140:143], v156 offset:61440
	ds_read_b128 v[80:83], v157 offset:57344
	ds_read_b128 v[148:151], v157 offset:61440
	s_waitcnt lgkmcnt(3)
	v_mfma_f32_16x16x32_bf16 v[72:75], v[72:75], v[58:61], 0
	s_waitcnt lgkmcnt(1)
	v_mfma_f32_16x16x32_bf16 v[72:75], v[80:83], v[54:57], v[72:75]
	ds_read_b128 v[80:83], v158 offset:57344
	ds_read_b128 v[152:155], v158 offset:61440
	s_waitcnt lgkmcnt(1)
	v_mfma_f32_16x16x32_bf16 v[72:75], v[80:83], v[62:65], v[72:75]
	ds_read_b128 v[80:83], v159 offset:57344
	ds_read_b128 v[156:159], v159 offset:61440
	s_waitcnt lgkmcnt(1)
	v_mfma_f32_16x16x32_bf16 v[80:83], v[80:83], v[50:53], v[72:75]
	v_mfma_f32_16x16x32_bf16 v[72:75], v[140:143], v[58:61], 0
	v_lshlrev_b32_e32 v142, 2, v118
	v_sub_u32_e32 v143, v119, v142
	v_exp_f32_e32 v140, v105
	v_mfma_f32_16x16x32_bf16 v[72:75], v[148:151], v[54:57], v[72:75]
	v_lshlrev_b32_e32 v141, 3, v118
	v_mul_f32_e32 v105, 0xbfb8aa3b, v104
	v_mul_f32_e32 v104, 0xbfb8aa3b, v140
	v_and_b32_e32 v141, 8, v141
	s_mov_b64 vcc, s[84:85]
	s_cbranch_vccnz .Lp3_maskdone
; __device__ __forceinline__ void ret_phase(const Params& P, LAS unsigned char* lds, int tid, int lane, int wave, int bid, int G) {
;     ...
;             for (int mt = 0; mt < 8; ++mt) {
;                 const f32x4 a = sa[mt];
;                 float e[4];
; #pragma unroll
;                 for (int i = 0; i < 4; ++i) { const int m = 16 * mt + 4 * g + i, df = n - m; const float f = __builtin_amdgcn_exp2f(df >= 0 ? lgf2 * (float)df : lgb2 * (float)(-df)); e[i] = a[i] * f; }
	v_subrev_u32_e32 v213, 0, v143
	v_sub_u32_e32 v218, 0, v143
	v_max_i32_e32 v218, v213, v218
	v_cvt_f32_u32_e32 v218, v218
	v_cmp_gt_i32_e32 vcc, 0, v213
	v_cndmask_b32_e32 v213, v105, v104, vcc
	v_mul_f32_e32 v213, v213, v218
	v_exp_f32_e32 v213, v213
	v_subrev_u32_e32 v219, 1, v143
	v_sub_u32_e32 v218, 1, v143
	v_max_i32_e32 v218, v219, v218
	v_cvt_f32_u32_e32 v218, v218
	v_cmp_gt_i32_e32 vcc, 0, v219
	v_cndmask_b32_e32 v219, v105, v104, vcc
	v_mul_f32_e32 v219, v219, v218
	v_exp_f32_e32 v219, v219
	v_subrev_u32_e32 v220, 2, v143
	v_sub_u32_e32 v218, 2, v143
	v_max_i32_e32 v218, v220, v218
	v_cvt_f32_u32_e32 v218, v218
	v_cmp_gt_i32_e32 vcc, 0, v220
	v_cndmask_b32_e32 v220, v105, v104, vcc
	v_mul_f32_e32 v220, v220, v218
	v_exp_f32_e32 v220, v220
	v_subrev_u32_e32 v221, 3, v143
	v_sub_u32_e32 v218, 3, v143
	v_max_i32_e32 v218, v221, v218
	v_cvt_f32_u32_e32 v218, v218
	v_cmp_gt_i32_e32 vcc, 0, v221
	v_cndmask_b32_e32 v221, v105, v104, vcc
	v_mul_f32_e32 v221, v221, v218
	v_exp_f32_e32 v221, v221
	v_subrev_u32_e32 v222, 16, v143
	v_sub_u32_e32 v218, 16, v143
	v_max_i32_e32 v218, v222, v218
	v_cvt_f32_u32_e32 v218, v218
	v_cmp_gt_i32_e32 vcc, 0, v222
	v_cndmask_b32_e32 v222, v105, v104, vcc
	v_mul_f32_e32 v222, v222, v218
	v_exp_f32_e32 v222, v222
	v_subrev_u32_e32 v223, 17, v143
	v_sub_u32_e32 v218, 17, v143
	v_max_i32_e32 v218, v223, v218
	v_cvt_f32_u32_e32 v218, v218
	v_cmp_gt_i32_e32 vcc, 0, v223
	v_cndmask_b32_e32 v223, v105, v104, vcc
	v_mul_f32_e32 v223, v223, v218
	v_exp_f32_e32 v223, v223
	v_subrev_u32_e32 v224, 18, v143
	v_sub_u32_e32 v218, 18, v143
	v_max_i32_e32 v218, v224, v218
	v_cvt_f32_u32_e32 v218, v218
	v_cmp_gt_i32_e32 vcc, 0, v224
	v_cndmask_b32_e32 v224, v105, v104, vcc
	v_mul_f32_e32 v224, v224, v218
	v_exp_f32_e32 v224, v224
	v_subrev_u32_e32 v225, 19, v143
	v_sub_u32_e32 v218, 19, v143
	v_max_i32_e32 v218, v225, v218
	v_cvt_f32_u32_e32 v218, v218
	v_cmp_gt_i32_e32 vcc, 0, v225
	v_cndmask_b32_e32 v225, v105, v104, vcc
	v_mul_f32_e32 v225, v225, v218
	v_exp_f32_e32 v225, v225
	v_subrev_u32_e32 v226, 32, v143
	v_sub_u32_e32 v218, 32, v143
	v_max_i32_e32 v218, v226, v218
	v_cvt_f32_u32_e32 v218, v218
	v_cmp_gt_i32_e32 vcc, 0, v226
	v_cndmask_b32_e32 v226, v105, v104, vcc
	v_mul_f32_e32 v226, v226, v218
	v_exp_f32_e32 v226, v226
	v_subrev_u32_e32 v227, 33, v143
	v_sub_u32_e32 v218, 33, v143
	v_max_i32_e32 v218, v227, v218
	v_cvt_f32_u32_e32 v218, v218
	v_cmp_gt_i32_e32 vcc, 0, v227
	v_cndmask_b32_e32 v227, v105, v104, vcc
	v_mul_f32_e32 v227, v227, v218
	v_exp_f32_e32 v227, v227
	v_subrev_u32_e32 v228, 34, v143
	v_sub_u32_e32 v218, 34, v143
	v_max_i32_e32 v218, v228, v218
	v_cvt_f32_u32_e32 v218, v218
	v_cmp_gt_i32_e32 vcc, 0, v228
	v_cndmask_b32_e32 v228, v105, v104, vcc
	v_mul_f32_e32 v228, v228, v218
	v_exp_f32_e32 v228, v228
	v_subrev_u32_e32 v229, 35, v143
	v_sub_u32_e32 v218, 35, v143
	v_max_i32_e32 v218, v229, v218
	v_cvt_f32_u32_e32 v218, v218
	v_cmp_gt_i32_e32 vcc, 0, v229
	v_cndmask_b32_e32 v229, v105, v104, vcc
	v_mul_f32_e32 v229, v229, v218
	v_exp_f32_e32 v229, v229
	v_subrev_u32_e32 v230, 48, v143
	v_sub_u32_e32 v218, 48, v143
	v_max_i32_e32 v218, v230, v218
	v_cvt_f32_u32_e32 v218, v218
	v_cmp_gt_i32_e32 vcc, 0, v230
	v_cndmask_b32_e32 v230, v105, v104, vcc
	v_mul_f32_e32 v230, v230, v218
	v_exp_f32_e32 v230, v230
	v_subrev_u32_e32 v231, 49, v143
	v_sub_u32_e32 v218, 49, v143
	v_max_i32_e32 v218, v231, v218
	v_cvt_f32_u32_e32 v218, v218
	v_cmp_gt_i32_e32 vcc, 0, v231
	v_cndmask_b32_e32 v231, v105, v104, vcc
	v_mul_f32_e32 v231, v231, v218
	v_exp_f32_e32 v231, v231
	v_subrev_u32_e32 v232, 50, v143
	v_sub_u32_e32 v218, 50, v143
	v_max_i32_e32 v218, v232, v218
	v_cvt_f32_u32_e32 v218, v218
	v_cmp_gt_i32_e32 vcc, 0, v232
	v_cndmask_b32_e32 v232, v105, v104, vcc
	v_mul_f32_e32 v232, v232, v218
	v_exp_f32_e32 v232, v232
	v_subrev_u32_e32 v233, 51, v143
	v_sub_u32_e32 v218, 51, v143
	v_max_i32_e32 v218, v233, v218
	v_cvt_f32_u32_e32 v218, v218
	v_cmp_gt_i32_e32 vcc, 0, v233
	v_cndmask_b32_e32 v233, v105, v104, vcc
	v_mul_f32_e32 v233, v233, v218
	v_exp_f32_e32 v233, v233
	v_subrev_u32_e32 v234, 64, v143
	v_sub_u32_e32 v218, 64, v143
	v_max_i32_e32 v218, v234, v218
	v_cvt_f32_u32_e32 v218, v218
	v_cmp_gt_i32_e32 vcc, 0, v234
	v_cndmask_b32_e32 v234, v105, v104, vcc
	v_mul_f32_e32 v234, v234, v218
	v_exp_f32_e32 v234, v234
	v_subrev_u32_e32 v235, 65, v143
	v_sub_u32_e32 v218, 65, v143
	v_max_i32_e32 v218, v235, v218
	v_cvt_f32_u32_e32 v218, v218
	v_cmp_gt_i32_e32 vcc, 0, v235
	v_cndmask_b32_e32 v235, v105, v104, vcc
	v_mul_f32_e32 v235, v235, v218
	v_exp_f32_e32 v235, v235
	v_subrev_u32_e32 v236, 66, v143
	v_sub_u32_e32 v218, 66, v143
	v_max_i32_e32 v218, v236, v218
	v_cvt_f32_u32_e32 v218, v218
	v_cmp_gt_i32_e32 vcc, 0, v236
	v_cndmask_b32_e32 v236, v105, v104, vcc
	v_mul_f32_e32 v236, v236, v218
	v_exp_f32_e32 v236, v236
	v_subrev_u32_e32 v237, 67, v143
	v_sub_u32_e32 v218, 67, v143
	v_max_i32_e32 v218, v237, v218
	v_cvt_f32_u32_e32 v218, v218
	v_cmp_gt_i32_e32 vcc, 0, v237
	v_cndmask_b32_e32 v237, v105, v104, vcc
	v_mul_f32_e32 v237, v237, v218
	v_exp_f32_e32 v237, v237
	v_subrev_u32_e32 v238, 80, v143
	v_sub_u32_e32 v218, 80, v143
	v_max_i32_e32 v218, v238, v218
	v_cvt_f32_u32_e32 v218, v218
	v_cmp_gt_i32_e32 vcc, 0, v238
	v_cndmask_b32_e32 v238, v105, v104, vcc
	v_mul_f32_e32 v238, v238, v218
	v_exp_f32_e32 v238, v238
	v_subrev_u32_e32 v239, 81, v143
	v_sub_u32_e32 v218, 81, v143
	v_max_i32_e32 v218, v239, v218
	v_cvt_f32_u32_e32 v218, v218
	v_cmp_gt_i32_e32 vcc, 0, v239
	v_cndmask_b32_e32 v239, v105, v104, vcc
	v_mul_f32_e32 v239, v239, v218
	v_exp_f32_e32 v239, v239
	v_subrev_u32_e32 v240, 82, v143
; __device__ __forceinline__ void ret_phase(const Params& P, LAS unsigned char* lds, int tid, int lane, int wave, int bid, int G) {
;     ...
;             for (int mt = 0; mt < 8; ++mt) {
;                 const f32x4 a = sa[mt];
;                 float e[4];
; #pragma unroll
;                 for (int i = 0; i < 4; ++i) { const int m = 16 * mt + 4 * g + i, df = n - m; const float f = __builtin_amdgcn_exp2f(df >= 0 ? lgf2 * (float)df : lgb2 * (float)(-df)); e[i] = a[i] * f; }
	v_sub_u32_e32 v218, 82, v143
	v_max_i32_e32 v218, v240, v218
	v_cvt_f32_u32_e32 v218, v218
	v_cmp_gt_i32_e32 vcc, 0, v240
	v_cndmask_b32_e32 v240, v105, v104, vcc
	v_mul_f32_e32 v240, v240, v218
	v_exp_f32_e32 v240, v240
	v_subrev_u32_e32 v241, 83, v143
	v_sub_u32_e32 v218, 83, v143
	v_max_i32_e32 v218, v241, v218
	v_cvt_f32_u32_e32 v218, v218
	v_cmp_gt_i32_e32 vcc, 0, v241
	v_cndmask_b32_e32 v241, v105, v104, vcc
	v_mul_f32_e32 v241, v241, v218
	v_exp_f32_e32 v241, v241
	v_subrev_u32_e32 v242, 96, v143
	v_sub_u32_e32 v218, 96, v143
	v_max_i32_e32 v218, v242, v218
	v_cvt_f32_u32_e32 v218, v218
	v_cmp_gt_i32_e32 vcc, 0, v242
	v_cndmask_b32_e32 v242, v105, v104, vcc
	v_mul_f32_e32 v242, v242, v218
	v_exp_f32_e32 v242, v242
	v_subrev_u32_e32 v243, 97, v143
	v_sub_u32_e32 v218, 97, v143
	v_max_i32_e32 v218, v243, v218
	v_cvt_f32_u32_e32 v218, v218
	v_cmp_gt_i32_e32 vcc, 0, v243
	v_cndmask_b32_e32 v243, v105, v104, vcc
	v_mul_f32_e32 v243, v243, v218
	v_exp_f32_e32 v243, v243
	v_subrev_u32_e32 v244, 98, v143
	v_sub_u32_e32 v218, 98, v143
	v_max_i32_e32 v218, v244, v218
	v_cvt_f32_u32_e32 v218, v218
	v_cmp_gt_i32_e32 vcc, 0, v244
	v_cndmask_b32_e32 v244, v105, v104, vcc
	v_mul_f32_e32 v244, v244, v218
	v_exp_f32_e32 v244, v244
	v_subrev_u32_e32 v245, 99, v143
	v_sub_u32_e32 v218, 99, v143
	v_max_i32_e32 v218, v245, v218
	v_cvt_f32_u32_e32 v218, v218
	v_cmp_gt_i32_e32 vcc, 0, v245
	v_cndmask_b32_e32 v245, v105, v104, vcc
	v_mul_f32_e32 v245, v245, v218
	v_exp_f32_e32 v245, v245
	v_subrev_u32_e32 v246, 112, v143
	v_sub_u32_e32 v218, 112, v143
	v_max_i32_e32 v218, v246, v218
	v_cvt_f32_u32_e32 v218, v218
	v_cmp_gt_i32_e32 vcc, 0, v246
	v_cndmask_b32_e32 v246, v105, v104, vcc
	v_mul_f32_e32 v246, v246, v218
	v_exp_f32_e32 v246, v246
	v_subrev_u32_e32 v247, 113, v143
	v_sub_u32_e32 v218, 113, v143
	v_max_i32_e32 v218, v247, v218
	v_cvt_f32_u32_e32 v218, v218
	v_cmp_gt_i32_e32 vcc, 0, v247
	v_cndmask_b32_e32 v247, v105, v104, vcc
	v_mul_f32_e32 v247, v247, v218
	v_exp_f32_e32 v247, v247
	v_subrev_u32_e32 v248, 114, v143
	v_sub_u32_e32 v218, 114, v143
	v_max_i32_e32 v218, v248, v218
	v_cvt_f32_u32_e32 v218, v218
	v_cmp_gt_i32_e32 vcc, 0, v248
	v_cndmask_b32_e32 v248, v105, v104, vcc
	v_mul_f32_e32 v248, v248, v218
	v_exp_f32_e32 v248, v248
	v_subrev_u32_e32 v249, 115, v143
	v_sub_u32_e32 v218, 115, v143
	v_max_i32_e32 v218, v249, v218
	v_cvt_f32_u32_e32 v218, v218
	v_cmp_gt_i32_e32 vcc, 0, v249
	v_cndmask_b32_e32 v249, v105, v104, vcc
	v_mul_f32_e32 v249, v249, v218
	v_exp_f32_e32 v249, v249
	s_mov_b64 s[84:85], s[86:87]
; __device__ __forceinline__ unsigned cvt_pk_bf16(float lo, float hi) { unsigned r; asm volatile("v_cvt_pk_bf16_f32 %0, %1, %2" : "=v"(r) : "v"(lo), "v"(hi)); return r; }
; #define LAS __attribute__((address_space(3)))
; #define LBAR() asm volatile("s_waitcnt lgkmcnt(0)\n\ts_barrier" ::: "memory")
; __device__ __forceinline__ void ret_phase(const Params& P, LAS unsigned char* lds, int tid, int lane, int wave, int bid, int G) {
;     ...
;             for (int mt = 0; mt < 8; ++mt) {
;                 const f32x4 a = sa[mt];
;                 float e[4];
; #pragma unroll
;                 for (int i = 0; i < 4; ++i) { const int m = 16 * mt + 4 * g + i, df = n - m; const float f = __builtin_amdgcn_exp2f(df >= 0 ? lgf2 * (float)df : lgb2 * (float)(-df)); e[i] = a[i] * f; }
;                 u32x2 w; w.x = cvt_pk_bf16(e[0], e[1]); w.y = cvt_pk_bf16(e[2], e[3]);
;                 *(LAS u32x2*)(Pt + off256(n, 2 * mt + (g >> 1)) + 8 * (g & 1)) = w;
;             }
;         }
;         LBAR();
;         u32x4 sfr[4], sbr[4];
; #pragma unroll
;         for (int j = 0; j < 2; ++j) { sfr[2 * j] = fp8x8_to_bf16x8(rsf[j].x, rsf[j].y); sfr[2 * j + 1] = fp8x8_to_bf16x8(rsf[j].z, rsf[j].w);
;             sbr[2 * j] = fp8x8_to_bf16x8(rsb[j].x, rsb[j].y); sbr[2 * j + 1] = fp8x8_to_bf16x8(rsb[j].z, rsb[j].w); }
;     ...
;         if (gc >= 512) {
;             const int k = (gc - 512) >> 5, j = gc & 31;
;             const float cf = exp2f(lgf2 * 128.f * (float)j), cb = exp2f(lgb2 * 128.f * (float)(31 - j)), df32 = exp2f(lgf2 * 4096.f), db32 = exp2f(lgb2 * 4096.f);
;             float wgt = cf;
.Lp3_maskdone:
	v_add3_u32 v135, s51, v135, v141
	v_lshrrev_b32_e32 v140, 1, v118
	v_mfma_f32_16x16x32_bf16 v[72:75], v[152:155], v[62:65], v[72:75]
	s_nop 7
	s_nop 7
	s_nop 7
	v_mul_f32_e32 v136, v213, v136
	v_mul_f32_e32 v137, v219, v137
	v_mul_f32_e32 v138, v220, v138
	v_cvt_pk_bf16_f32 v136, v136, v137
	v_mul_f32_e32 v119, v221, v139
	v_cvt_pk_bf16_f32 v137, v138, v119
	v_bitop3_b32 v119, v66, v140, v67 bitop3:0x36
	v_lshl_add_u32 v119, v119, 4, v135
	ds_write_b64 v119, v[136:137]
	s_nop 7
	s_nop 7
	s_nop 7
	v_mul_f32_e32 v119, v222, v122
	v_mul_f32_e32 v122, v223, v123
	v_cvt_pk_bf16_f32 v122, v119, v122
	v_add_u32_e32 v119, 2, v140
	v_mul_f32_e32 v123, v224, v124
	v_bitop3_b32 v119, v66, v119, v67 bitop3:0x36
	v_mul_f32_e32 v124, v225, v125
	v_cvt_pk_bf16_f32 v123, v123, v124
	v_lshl_add_u32 v119, v119, 4, v135
	ds_write_b64 v119, v[122:123]
	s_nop 7
	s_nop 7
	s_nop 7
	v_mul_f32_e32 v119, v226, v144
	v_mul_f32_e32 v122, v227, v145
	v_cvt_pk_bf16_f32 v122, v119, v122
	v_add_u32_e32 v119, 4, v140
	v_mul_f32_e32 v123, v228, v146
	v_bitop3_b32 v119, v66, v119, v67 bitop3:0x36
	v_mul_f32_e32 v124, v229, v147
	v_cvt_pk_bf16_f32 v123, v123, v124
	v_lshl_add_u32 v119, v119, 4, v135
	ds_write_b64 v119, v[122:123]
	s_nop 7
	s_nop 7
	s_nop 7
	v_mul_f32_e32 v100, v230, v100
	v_mul_f32_e32 v101, v231, v101
	v_mul_f32_e32 v102, v232, v102
	v_mul_f32_e32 v103, v233, v103
	v_cvt_pk_bf16_f32 v100, v100, v101
	v_cvt_pk_bf16_f32 v101, v102, v103
	v_add_u32_e32 v102, 6, v140
	v_bitop3_b32 v102, v66, v102, v67 bitop3:0x36
	v_lshl_add_u32 v102, v102, 4, v135
	ds_write_b64 v102, v[100:101]
	s_nop 7
	s_nop 7
	s_nop 7
	v_mul_f32_e32 v96, v234, v96
	v_mul_f32_e32 v97, v235, v97
	v_mul_f32_e32 v98, v236, v98
	v_mul_f32_e32 v99, v237, v99
	v_cvt_pk_bf16_f32 v96, v96, v97
	v_cvt_pk_bf16_f32 v97, v98, v99
	v_add_u32_e32 v98, 8, v140
	v_bitop3_b32 v98, v66, v98, v67 bitop3:0x36
	v_lshl_add_u32 v98, v98, 4, v135
	ds_write_b64 v98, v[96:97]
	s_nop 7
	s_nop 7
	s_nop 7
	v_mul_f32_e32 v88, v238, v88
	v_mul_f32_e32 v89, v239, v89
	v_mul_f32_e32 v90, v240, v90
	v_mul_f32_e32 v91, v241, v91
	v_cvt_pk_bf16_f32 v88, v88, v89
	v_cvt_pk_bf16_f32 v89, v90, v91
	v_add_u32_e32 v90, 10, v140
	v_bitop3_b32 v90, v66, v90, v67 bitop3:0x36
	v_lshl_add_u32 v90, v90, 4, v135
	ds_write_b64 v90, v[88:89]
	s_nop 7
	s_nop 7
	s_nop 7
	v_mul_f32_e32 v80, v242, v80
	v_mul_f32_e32 v81, v243, v81
	v_mul_f32_e32 v82, v244, v82
	v_mul_f32_e32 v83, v245, v83
	v_cvt_pk_bf16_f32 v80, v80, v81
	v_cvt_pk_bf16_f32 v81, v82, v83
	v_add_u32_e32 v82, 12, v140
	v_bitop3_b32 v82, v66, v82, v67 bitop3:0x36
	v_lshl_add_u32 v82, v82, 4, v135
	ds_write_b64 v82, v[80:81]
	s_waitcnt lgkmcnt(7)
	v_mfma_f32_16x16x32_bf16 v[72:75], v[156:159], v[50:53], v[72:75]
	s_nop 1
	s_nop 7
	s_nop 7
	s_nop 7
	v_mul_f32_e32 v72, v246, v72
	v_mul_f32_e32 v73, v247, v73
	v_mul_f32_e32 v74, v248, v74
	v_mul_f32_e32 v75, v249, v75
	v_cvt_pk_bf16_f32 v72, v72, v73
	v_cvt_pk_bf16_f32 v73, v74, v75
	v_add_u32_e32 v74, 14, v140
	v_bitop3_b32 v66, v66, v74, v67 bitop3:0x36
	v_lshl_add_u32 v66, v66, 4, v135
	ds_write_b64 v66, v[72:73]
	s_waitcnt vmcnt(3)
	v_cvt_pk_f32_fp8_e32 v[66:67], v68
	v_cvt_pk_f32_fp8_sdwa v[72:73], v68 src0_sel:WORD_1
	v_cvt_pk_f32_fp8_e32 v[74:75], v69
	v_cvt_pk_f32_fp8_sdwa v[80:81], v69 src0_sel:WORD_1
	s_waitcnt lgkmcnt(0)
	s_barrier
	v_cvt_pk_bf16_f32 v66, v66, v67
	v_cvt_pk_bf16_f32 v67, v72, v73
	v_cvt_pk_bf16_f32 v68, v74, v75
	v_cvt_pk_bf16_f32 v69, v80, v81
	v_cvt_pk_f32_fp8_e32 v[72:73], v70
	v_cvt_pk_f32_fp8_sdwa v[74:75], v70 src0_sel:WORD_1
	v_cvt_pk_f32_fp8_e32 v[80:81], v71
	v_cvt_pk_f32_fp8_sdwa v[82:83], v71 src0_sel:WORD_1
	v_cvt_pk_bf16_f32 v70, v72, v73
	v_cvt_pk_bf16_f32 v71, v74, v75
	v_cvt_pk_bf16_f32 v72, v80, v81
	v_cvt_pk_bf16_f32 v73, v82, v83
	s_waitcnt vmcnt(2)
	v_cvt_pk_f32_fp8_e32 v[74:75], v76
	v_cvt_pk_f32_fp8_sdwa v[80:81], v76 src0_sel:WORD_1
	v_cvt_pk_f32_fp8_e32 v[82:83], v77
	v_cvt_pk_f32_fp8_sdwa v[88:89], v77 src0_sel:WORD_1
	v_cvt_pk_bf16_f32 v74, v74, v75
	v_cvt_pk_bf16_f32 v75, v80, v81
	v_cvt_pk_bf16_f32 v76, v82, v83
	v_cvt_pk_bf16_f32 v77, v88, v89
	v_cvt_pk_f32_fp8_e32 v[80:81], v78
	v_cvt_pk_f32_fp8_sdwa v[82:83], v78 src0_sel:WORD_1
	v_cvt_pk_f32_fp8_e32 v[88:89], v79
	v_cvt_pk_f32_fp8_sdwa v[90:91], v79 src0_sel:WORD_1
	v_cvt_pk_bf16_f32 v78, v80, v81
	v_cvt_pk_bf16_f32 v79, v82, v83
	v_cvt_pk_bf16_f32 v80, v88, v89
	v_cvt_pk_bf16_f32 v81, v90, v91
	s_waitcnt vmcnt(1)
	v_cvt_pk_f32_fp8_e32 v[82:83], v84
	v_cvt_pk_f32_fp8_sdwa v[88:89], v84 src0_sel:WORD_1
	v_cvt_pk_f32_fp8_e32 v[90:91], v85
	v_cvt_pk_f32_fp8_sdwa v[96:97], v85 src0_sel:WORD_1
	v_cvt_pk_bf16_f32 v82, v82, v83
	v_cvt_pk_bf16_f32 v83, v88, v89
	v_cvt_pk_bf16_f32 v84, v90, v91
	v_cvt_pk_bf16_f32 v85, v96, v97
	v_cvt_pk_f32_fp8_e32 v[88:89], v86
	v_cvt_pk_f32_fp8_sdwa v[90:91], v86 src0_sel:WORD_1
	v_cvt_pk_f32_fp8_e32 v[96:97], v87
	v_cvt_pk_f32_fp8_sdwa v[98:99], v87 src0_sel:WORD_1
	v_cvt_pk_bf16_f32 v86, v88, v89
	v_cvt_pk_bf16_f32 v87, v90, v91
	v_cvt_pk_bf16_f32 v88, v96, v97
	s_waitcnt vmcnt(0)
	v_cvt_pk_f32_fp8_e32 v[90:91], v92
	v_cvt_pk_f32_fp8_sdwa v[96:97], v92 src0_sel:WORD_1
	v_cvt_pk_bf16_f32 v89, v98, v99
	v_cvt_pk_f32_fp8_e32 v[98:99], v93
	v_cvt_pk_f32_fp8_sdwa v[100:101], v93 src0_sel:WORD_1
	v_cvt_pk_bf16_f32 v90, v90, v91
	v_cvt_pk_bf16_f32 v91, v96, v97
	v_cvt_pk_f32_fp8_e32 v[96:97], v94
	v_cvt_pk_bf16_f32 v92, v98, v99
	v_cvt_pk_bf16_f32 v93, v100, v101
	v_cvt_pk_f32_fp8_sdwa v[98:99], v94 src0_sel:WORD_1
	v_cvt_pk_f32_fp8_e32 v[100:101], v95
	v_cvt_pk_f32_fp8_sdwa v[102:103], v95 src0_sel:WORD_1
	v_cvt_pk_bf16_f32 v94, v96, v97
	v_cvt_pk_bf16_f32 v95, v98, v99
	v_cvt_pk_bf16_f32 v96, v100, v101
	v_cvt_pk_bf16_f32 v97, v102, v103
	s_cbranch_scc1 .LBB0_391
	s_add_i32 s34, s40, 0xfffffe00
	s_and_b32 s5, s56, 3
	s_lshr_b32 s4, s34, 5
	s_bfe_u32 s27, s26, 0x50002
	s_cmp_lt_u32 s34, 32
	s_cbranch_scc1 .LBB0_388
	v_mul_f32_e32 v98, 0x45800000, v105
	v_cmp_gt_f32_e32 vcc, s52, v98
	v_mul_f32_e32 v99, 0x43000000, v105
	v_cvt_f32_ubyte0_e32 v100, s27
	v_cndmask_b32_e32 v98, 0, v132, vcc
	v_mul_f32_e32 v101, v99, v100
	s_and_b64 s[0:1], vcc, exec
	v_fmac_f32_e32 v98, 0x45800000, v105
	v_cmp_gt_f32_e32 vcc, s52, v101
	v_exp_f32_e32 v98, v98
	s_cselect_b32 s0, 0xffffffc0, 0
	v_cndmask_b32_e32 v101, 0, v132, vcc
	v_fmac_f32_e32 v101, v99, v100
	v_exp_f32_e32 v99, v101
	v_ldexp_f32 v98, v98, s0
	s_and_b64 s[0:1], vcc, exec
	s_cselect_b32 s0, 0xffffffc0, 0
	v_ldexp_f32 v99, v99, s0
	s_lshl_b32 s0, s4, 2
	s_or_b32 s0, s0, s5
	s_add_i32 s18, s0, 60
	s_add_i32 s35, s4, 1
